# sliding-window units skip the second-value-half PV block (its result was discarded)
# baseline (speedup 1.0000x reference)
.LBB0_430:
	s_or_b64 exec, exec, s[66:67]
	s_waitcnt lgkmcnt(14)
	v_mfma_f32_32x32x16_bf16 v[18:33], v[142:145], v[84:87], v[18:33]
	v_exp_f32_e32 v66, v66
	v_exp_f32_e32 v67, v67
	v_exp_f32_e32 v68, v68
	v_exp_f32_e32 v69, v69
	s_waitcnt lgkmcnt(12)
	v_mfma_f32_32x32x16_bf16 v[34:49], v[142:145], v[88:91], v[34:49]
	v_exp_f32_e32 v70, v70
	v_exp_f32_e32 v71, v71
	v_exp_f32_e32 v72, v72
	v_exp_f32_e32 v73, v73
	v_add_u32_e32 v84, s87, v231
	ds_read_b128 v[174:177], v84
	ds_read_b128 v[170:173], v84 offset:512
	s_waitcnt lgkmcnt(12)
	v_mfma_f32_32x32x16_bf16 v[18:33], v[138:141], v[92:95], v[18:33]
	v_exp_f32_e32 v74, v74
	v_exp_f32_e32 v75, v75
	v_exp_f32_e32 v76, v76
	v_exp_f32_e32 v77, v77
	ds_read_b128 v[166:169], v84 offset:2048
	ds_read_b128 v[162:165], v84 offset:2560
	s_waitcnt lgkmcnt(12)
	v_mfma_f32_32x32x16_bf16 v[34:49], v[138:141], v[114:117], v[34:49]
	v_exp_f32_e32 v78, v78
	v_exp_f32_e32 v79, v79
	v_exp_f32_e32 v80, v80
	v_exp_f32_e32 v81, v81
	ds_read_b128 v[158:161], v84 offset:4096
	ds_read_b128 v[154:157], v84 offset:4608
	s_waitcnt lgkmcnt(12)
	v_mfma_f32_32x32x16_bf16 v[18:33], v[134:137], v[118:121], v[18:33]
	v_exp_f32_e32 v50, v50
	v_exp_f32_e32 v51, v51
	v_exp_f32_e32 v52, v52
	v_exp_f32_e32 v53, v53
	ds_read_b128 v[150:153], v84 offset:6144
	ds_read_b128 v[146:149], v84 offset:6656
	s_waitcnt lgkmcnt(12)
	v_mfma_f32_32x32x16_bf16 v[34:49], v[134:137], v[96:99], v[34:49]
	v_exp_f32_e32 v54, v54
	v_exp_f32_e32 v55, v55
	v_exp_f32_e32 v56, v56
	v_exp_f32_e32 v57, v57
	s_waitcnt lgkmcnt(10)
	v_mfma_f32_32x32x16_bf16 v[18:33], v[130:133], v[100:103], v[18:33]
	v_exp_f32_e32 v58, v58
	v_exp_f32_e32 v59, v59
	v_exp_f32_e32 v60, v60
	v_exp_f32_e32 v61, v61
	s_waitcnt lgkmcnt(8)
	v_mfma_f32_32x32x16_bf16 v[34:49], v[130:133], v[104:107], v[34:49]
	v_exp_f32_e32 v62, v62
	v_exp_f32_e32 v63, v63
	v_exp_f32_e32 v64, v64
	v_exp_f32_e32 v65, v65
	s_cmp_lg_u32 s62, 0
	s_cbranch_scc1 .Lmy_nt_11741
	ds_read_b64_tr_b16 v[98:99], v255 offset:24576
	ds_read_b64_tr_b16 v[100:101], v255 offset:25088
	ds_read_b64_tr_b16 v[102:103], v255 offset:28672
	ds_read_b64_tr_b16 v[104:105], v255 offset:29184
	ds_read_b64_tr_b16 v[106:107], v255 offset:25600
	ds_read_b64_tr_b16 v[108:109], v255 offset:26112
	ds_read_b64_tr_b16 v[110:111], v255 offset:29696
	ds_read_b64_tr_b16 v[112:113], v255 offset:30208
	ds_read_b64_tr_b16 v[114:115], v255 offset:26624
	ds_read_b64_tr_b16 v[116:117], v255 offset:27136
	ds_read_b64_tr_b16 v[118:119], v255 offset:30720
	ds_read_b64_tr_b16 v[120:121], v255 offset:31232
	ds_read_b64_tr_b16 v[122:123], v255 offset:27648
	ds_read_b64_tr_b16 v[124:125], v255 offset:28160
	ds_read_b64_tr_b16 v[126:127], v255 offset:31744
	ds_read_b64_tr_b16 v[128:129], v255 offset:32256
	s_waitcnt lgkmcnt(14)
	v_mfma_f32_32x32x16_bf16 v[236:251], v[142:145], v[98:101], v[236:251]
	s_waitcnt lgkmcnt(12)
	v_mfma_f32_32x32x16_bf16 v[200:215], v[142:145], v[102:105], v[200:215]
	s_waitcnt lgkmcnt(10)
	v_mfma_f32_32x32x16_bf16 v[236:251], v[138:141], v[106:109], v[236:251]
	s_waitcnt lgkmcnt(8)
	v_mfma_f32_32x32x16_bf16 v[200:215], v[138:141], v[110:113], v[200:215]
	s_waitcnt lgkmcnt(6)
	v_mfma_f32_32x32x16_bf16 v[236:251], v[134:137], v[114:117], v[236:251]
	s_waitcnt lgkmcnt(4)
	v_mfma_f32_32x32x16_bf16 v[200:215], v[134:137], v[118:121], v[200:215]
	s_waitcnt lgkmcnt(2)
	v_mfma_f32_32x32x16_bf16 v[236:251], v[130:133], v[122:125], v[236:251]
	s_waitcnt lgkmcnt(0)
	v_mfma_f32_32x32x16_bf16 v[200:215], v[130:133], v[126:129], v[200:215]
.Lmy_nt_11741:
	s_sub_i32 s66, s49, 64
	v_cvt_f32_u32_e32 v84, s66
	v_mov_b32_e32 v185, v184
	s_mov_b64 s[66:67], -1
	s_and_b64 vcc, exec, s[64:65]
	v_fma_f32 v84, v184, v84, v186
	v_sub_f32_e32 v84, v84, v225
	v_fma_f32 v114, 0, v184, v84
	v_add_f32_e32 v115, v184, v84
	v_fma_f32 v117, v191, s9, v84
	v_fma_f32 v116, v190, s8, v84
	v_fma_f32 v119, v191, s11, v84
	v_fma_f32 v118, v190, s10, v84
	v_fma_f32 v121, v191, s13, v84
	v_fma_f32 v120, v190, s12, v84
	v_fma_f32 v123, v191, s15, v84
	v_fma_f32 v122, v190, s14, v84
	v_fma_f32 v125, v191, s17, v84
	v_fma_f32 v124, v190, s16, v84
	v_fma_f32 v127, v191, s19, v84
	v_fma_f32 v126, v190, s18, v84
	v_fma_f32 v129, v191, s21, v84
	v_fma_f32 v128, v190, s20, v84
	v_fma_f32 v113, v185, s23, v84
	v_fma_f32 v112, v184, s22, v84
	v_fma_f32 v111, v185, s25, v84
	v_fma_f32 v110, v184, s24, v84
	v_fma_f32 v109, v185, s27, v84
	v_fma_f32 v108, v184, s26, v84
	v_fma_f32 v107, v185, s29, v84
	v_fma_f32 v106, v184, s28, v84
	v_fma_f32 v105, v185, s31, v84
	v_fma_f32 v104, v184, s30, v84
	v_fma_f32 v103, v185, s35, v84
	v_fma_f32 v102, v184, s34, v84
	v_fma_f32 v101, v185, s37, v84
	v_fma_f32 v100, v184, s36, v84
	v_fma_f32 v99, v189, s93, v84
	v_fma_f32 v98, v188, s92, v84
	s_nop 0
	s_cbranch_vccnz .LBB0_520
	s_andn2_b64 vcc, exec, s[66:67]
	s_cbranch_vccz .LBB0_525

.LBB0_514:
	s_waitcnt lgkmcnt(4)
	v_mfma_f32_32x32x16_bf16 v[34:49], v[134:137], v[66:69], v[34:49]
	v_exp_f32_e32 v102, v102
	v_exp_f32_e32 v103, v103
	v_exp_f32_e32 v104, v104
	v_exp_f32_e32 v105, v105
	s_waitcnt lgkmcnt(2)
	v_mfma_f32_32x32x16_bf16 v[18:33], v[130:133], v[54:57], v[18:33]
	v_exp_f32_e32 v106, v106
	v_exp_f32_e32 v107, v107
	v_exp_f32_e32 v108, v108
	v_exp_f32_e32 v109, v109
	s_waitcnt lgkmcnt(0)
	v_mfma_f32_32x32x16_bf16 v[34:49], v[130:133], v[50:53], v[34:49]
	v_exp_f32_e32 v110, v110
	v_exp_f32_e32 v111, v111
	v_exp_f32_e32 v112, v112
	v_exp_f32_e32 v113, v113
	s_cmp_lg_u32 s62, 0
	s_cbranch_scc1 .Lmy_nt_12418
	ds_read_b64_tr_b16 v[50:51], v255 offset:24576
	ds_read_b64_tr_b16 v[52:53], v255 offset:25088
	ds_read_b64_tr_b16 v[54:55], v255 offset:28672
	ds_read_b64_tr_b16 v[56:57], v255 offset:29184
	ds_read_b64_tr_b16 v[58:59], v255 offset:25600
	ds_read_b64_tr_b16 v[60:61], v255 offset:26112
	ds_read_b64_tr_b16 v[62:63], v255 offset:29696
	ds_read_b64_tr_b16 v[64:65], v255 offset:30208
	ds_read_b64_tr_b16 v[66:67], v255 offset:26624
	ds_read_b64_tr_b16 v[68:69], v255 offset:27136
	ds_read_b64_tr_b16 v[70:71], v255 offset:30720
	ds_read_b64_tr_b16 v[72:73], v255 offset:31232
	ds_read_b64_tr_b16 v[74:75], v255 offset:27648
	ds_read_b64_tr_b16 v[76:77], v255 offset:28160
	ds_read_b64_tr_b16 v[78:79], v255 offset:31744
	ds_read_b64_tr_b16 v[80:81], v255 offset:32256
	s_waitcnt lgkmcnt(14)
	v_mfma_f32_32x32x16_bf16 v[236:251], v[142:145], v[50:53], v[236:251]
	s_waitcnt lgkmcnt(12)
	v_mfma_f32_32x32x16_bf16 v[200:215], v[142:145], v[54:57], v[200:215]
	s_waitcnt lgkmcnt(10)
	v_mfma_f32_32x32x16_bf16 v[236:251], v[138:141], v[58:61], v[236:251]
	s_waitcnt lgkmcnt(8)
	v_mfma_f32_32x32x16_bf16 v[200:215], v[138:141], v[62:65], v[200:215]
	s_waitcnt lgkmcnt(6)
	v_mfma_f32_32x32x16_bf16 v[236:251], v[134:137], v[66:69], v[236:251]
	s_waitcnt lgkmcnt(4)
	v_mfma_f32_32x32x16_bf16 v[200:215], v[134:137], v[70:73], v[200:215]
	s_waitcnt lgkmcnt(2)
	v_mfma_f32_32x32x16_bf16 v[236:251], v[130:133], v[74:77], v[236:251]
	s_waitcnt lgkmcnt(0)
	v_mfma_f32_32x32x16_bf16 v[200:215], v[130:133], v[78:81], v[200:215]
.Lmy_nt_12418:
	v_cvt_f32_i32_e32 v50, s49
	v_mov_b32_e32 v185, v184
	s_mov_b64 s[44:45], -1
	s_and_b64 vcc, exec, s[66:67]
	v_fma_f32 v50, v184, v50, v186
	v_sub_f32_e32 v50, v50, v225
	v_fma_f32 v66, 0, v184, v50
	v_add_f32_e32 v67, v184, v50
	v_fma_f32 v69, v191, s9, v50
	v_fma_f32 v68, v190, s8, v50
	v_fma_f32 v71, v191, s11, v50
	v_fma_f32 v70, v190, s10, v50
	v_fma_f32 v73, v191, s13, v50
	v_fma_f32 v72, v190, s12, v50
	v_fma_f32 v75, v191, s15, v50
	v_fma_f32 v74, v190, s14, v50
	v_fma_f32 v77, v191, s17, v50
	v_fma_f32 v76, v190, s16, v50
	v_fma_f32 v79, v191, s19, v50
	v_fma_f32 v78, v190, s18, v50
	v_fma_f32 v81, v191, s21, v50
	v_fma_f32 v80, v190, s20, v50
	v_fma_f32 v65, v185, s23, v50
	v_fma_f32 v64, v184, s22, v50
	v_fma_f32 v63, v185, s25, v50
	v_fma_f32 v62, v184, s24, v50
	v_fma_f32 v61, v185, s27, v50
	v_fma_f32 v60, v184, s26, v50
	v_fma_f32 v59, v185, s29, v50
	v_fma_f32 v58, v184, s28, v50
	v_fma_f32 v57, v185, s31, v50
	v_fma_f32 v56, v184, s30, v50
	v_fma_f32 v55, v185, s35, v50
	v_fma_f32 v54, v184, s34, v50
	v_fma_f32 v53, v185, s37, v50
	v_fma_f32 v52, v184, s36, v50
	v_fma_f32 v51, v189, s93, v50
	v_fma_f32 v50, v188, s92, v50
	s_nop 0
	s_cbranch_vccnz .LBB0_526
	s_andn2_b64 vcc, exec, s[44:45]
	s_cbranch_vccz .LBB0_531

.LBB0_607:
	s_or_b64 exec, exec, s[42:43]
	s_waitcnt lgkmcnt(14)
	v_mfma_f32_32x32x16_bf16 v[18:33], v[142:145], v[84:87], v[18:33]
	v_exp_f32_e32 v66, v66
	v_exp_f32_e32 v67, v67
	v_exp_f32_e32 v68, v68
	v_exp_f32_e32 v69, v69
	s_waitcnt lgkmcnt(12)
	v_mfma_f32_32x32x16_bf16 v[34:49], v[142:145], v[88:91], v[34:49]
	v_exp_f32_e32 v70, v70
	v_exp_f32_e32 v71, v71
	v_exp_f32_e32 v72, v72
	v_exp_f32_e32 v73, v73
	s_waitcnt lgkmcnt(10)
	v_mfma_f32_32x32x16_bf16 v[18:33], v[138:141], v[92:95], v[18:33]
	v_exp_f32_e32 v74, v74
	v_exp_f32_e32 v75, v75
	v_exp_f32_e32 v76, v76
	v_exp_f32_e32 v77, v77
	s_waitcnt lgkmcnt(8)
	v_mfma_f32_32x32x16_bf16 v[34:49], v[138:141], v[114:117], v[34:49]
	v_exp_f32_e32 v78, v78
	v_exp_f32_e32 v79, v79
	v_exp_f32_e32 v80, v80
	v_exp_f32_e32 v81, v81
	s_waitcnt lgkmcnt(6)
	v_mfma_f32_32x32x16_bf16 v[18:33], v[134:137], v[118:121], v[18:33]
	v_exp_f32_e32 v50, v50
	v_exp_f32_e32 v51, v51
	v_exp_f32_e32 v52, v52
	v_exp_f32_e32 v53, v53
	s_waitcnt lgkmcnt(4)
	v_mfma_f32_32x32x16_bf16 v[34:49], v[134:137], v[96:99], v[34:49]
	v_exp_f32_e32 v54, v54
	v_exp_f32_e32 v55, v55
	v_exp_f32_e32 v56, v56
	v_exp_f32_e32 v57, v57
	s_waitcnt lgkmcnt(2)
	v_mfma_f32_32x32x16_bf16 v[18:33], v[130:133], v[100:103], v[18:33]
	v_exp_f32_e32 v58, v58
	v_exp_f32_e32 v59, v59
	v_exp_f32_e32 v60, v60
	v_exp_f32_e32 v61, v61
	s_waitcnt lgkmcnt(0)
	v_mfma_f32_32x32x16_bf16 v[34:49], v[130:133], v[104:107], v[34:49]
	v_exp_f32_e32 v62, v62
	v_exp_f32_e32 v63, v63
	v_exp_f32_e32 v64, v64
	v_exp_f32_e32 v65, v65
	s_cmp_lg_u32 s62, 0
	s_cbranch_scc1 .Lmy_nt_13191
	ds_read_b64_tr_b16 v[82:83], v255 offset:24576
	ds_read_b64_tr_b16 v[84:85], v255 offset:25088
	ds_read_b64_tr_b16 v[86:87], v255 offset:28672
	ds_read_b64_tr_b16 v[88:89], v255 offset:29184
	ds_read_b64_tr_b16 v[90:91], v255 offset:25600
	ds_read_b64_tr_b16 v[92:93], v255 offset:26112
	ds_read_b64_tr_b16 v[94:95], v255 offset:29696
	ds_read_b64_tr_b16 v[96:97], v255 offset:30208
	ds_read_b64_tr_b16 v[98:99], v255 offset:26624
	ds_read_b64_tr_b16 v[100:101], v255 offset:27136
	ds_read_b64_tr_b16 v[102:103], v255 offset:30720
	ds_read_b64_tr_b16 v[104:105], v255 offset:31232
	ds_read_b64_tr_b16 v[106:107], v255 offset:27648
	ds_read_b64_tr_b16 v[108:109], v255 offset:28160
	ds_read_b64_tr_b16 v[110:111], v255 offset:31744
	ds_read_b64_tr_b16 v[112:113], v255 offset:32256
	s_waitcnt lgkmcnt(14)
	v_mfma_f32_32x32x16_bf16 v[236:251], v[142:145], v[82:85], v[236:251]
	s_waitcnt lgkmcnt(12)
	v_mfma_f32_32x32x16_bf16 v[200:215], v[142:145], v[86:89], v[200:215]
	s_waitcnt lgkmcnt(10)
	v_mfma_f32_32x32x16_bf16 v[236:251], v[138:141], v[90:93], v[236:251]
	s_waitcnt lgkmcnt(8)
	v_mfma_f32_32x32x16_bf16 v[200:215], v[138:141], v[94:97], v[200:215]
	s_waitcnt lgkmcnt(6)
	v_mfma_f32_32x32x16_bf16 v[236:251], v[134:137], v[98:101], v[236:251]
	s_waitcnt lgkmcnt(4)
	v_mfma_f32_32x32x16_bf16 v[200:215], v[134:137], v[102:105], v[200:215]
	s_waitcnt lgkmcnt(2)
	v_mfma_f32_32x32x16_bf16 v[236:251], v[130:133], v[106:109], v[236:251]
	s_waitcnt lgkmcnt(0)
	v_mfma_f32_32x32x16_bf16 v[200:215], v[130:133], v[110:113], v[200:215]
.Lmy_nt_13191:
	v_cvt_f32_i32_e32 v82, s4
	v_mov_b32_e32 v185, v184
	v_fmac_f32_e32 v186, v184, v82
	v_sub_f32_e32 v98, v186, v225
	v_fma_f32 v82, 0, v184, v98
	v_add_f32_e32 v83, v184, v98
	v_pk_fma_f32 v[84:85], v[190:191], s[8:9], v[98:99] op_sel_hi:[1,1,0]
	v_pk_fma_f32 v[86:87], v[190:191], s[10:11], v[98:99] op_sel_hi:[1,1,0]
	v_pk_fma_f32 v[88:89], v[190:191], s[12:13], v[98:99] op_sel_hi:[1,1,0]
	v_pk_fma_f32 v[90:91], v[190:191], s[14:15], v[98:99] op_sel_hi:[1,1,0]
	v_pk_fma_f32 v[92:93], v[190:191], s[16:17], v[98:99] op_sel_hi:[1,1,0]
	v_pk_fma_f32 v[94:95], v[190:191], s[18:19], v[98:99] op_sel_hi:[1,1,0]
	v_pk_fma_f32 v[96:97], v[190:191], s[20:21], v[98:99] op_sel_hi:[1,1,0]
	v_pk_fma_f32 v[112:113], v[184:185], s[22:23], v[98:99] op_sel_hi:[1,1,0]
	v_pk_fma_f32 v[110:111], v[184:185], s[24:25], v[98:99] op_sel_hi:[1,1,0]
	v_pk_fma_f32 v[108:109], v[184:185], s[26:27], v[98:99] op_sel_hi:[1,1,0]
	v_pk_fma_f32 v[106:107], v[184:185], s[28:29], v[98:99] op_sel_hi:[1,1,0]
	v_pk_fma_f32 v[104:105], v[184:185], s[30:31], v[98:99] op_sel_hi:[1,1,0]
	v_pk_fma_f32 v[102:103], v[184:185], s[34:35], v[98:99] op_sel_hi:[1,1,0]
	v_pk_fma_f32 v[100:101], v[184:185], s[36:37], v[98:99] op_sel_hi:[1,1,0]
	v_pk_fma_f32 v[98:99], v[188:189], s[92:93], v[98:99] op_sel_hi:[1,1,0]
	s_nop 0
	s_and_saveexec_b64 s[40:41], s[38:39]
	s_cbranch_execz .LBB0_609
	s_waitcnt lgkmcnt(0)
	ds_read_b128 v[82:85], v227 offset:49248
	ds_read_b128 v[86:89], v227 offset:49216
	ds_read_b128 v[90:93], v227 offset:49184
	s_waitcnt lgkmcnt(2)
	v_pk_mul_f32 v[32:33], v[32:33], v[84:85]
	v_pk_mul_f32 v[30:31], v[30:31], v[82:83]
	v_pk_mul_f32 v[48:49], v[48:49], v[84:85]
	v_pk_mul_f32 v[46:47], v[46:47], v[82:83]
	v_pk_mul_f32 v[250:251], v[250:251], v[84:85]
	v_pk_mul_f32 v[248:249], v[248:249], v[82:83]
	v_pk_mul_f32 v[214:215], v[214:215], v[84:85]
	v_pk_mul_f32 v[212:213], v[212:213], v[82:83]
	ds_read_b128 v[82:85], v227 offset:49152
	s_waitcnt lgkmcnt(2)
	v_pk_mul_f32 v[28:29], v[28:29], v[88:89]
	v_pk_mul_f32 v[26:27], v[26:27], v[86:87]
	v_pk_mul_f32 v[44:45], v[44:45], v[88:89]
	v_pk_mul_f32 v[42:43], v[42:43], v[86:87]
	v_pk_mul_f32 v[246:247], v[246:247], v[88:89]
	v_pk_mul_f32 v[244:245], v[244:245], v[86:87]
	v_pk_mul_f32 v[210:211], v[210:211], v[88:89]
	v_pk_mul_f32 v[208:209], v[208:209], v[86:87]
	s_waitcnt lgkmcnt(1)
	v_pk_mul_f32 v[24:25], v[24:25], v[92:93]
	v_pk_mul_f32 v[22:23], v[22:23], v[90:91]
	v_pk_mul_f32 v[40:41], v[40:41], v[92:93]
	v_pk_mul_f32 v[38:39], v[38:39], v[90:91]
	v_pk_mul_f32 v[242:243], v[242:243], v[92:93]
	v_pk_mul_f32 v[240:241], v[240:241], v[90:91]
	v_pk_mul_f32 v[206:207], v[206:207], v[92:93]
	v_pk_mul_f32 v[204:205], v[204:205], v[90:91]
	s_waitcnt lgkmcnt(0)
	v_pk_mul_f32 v[20:21], v[20:21], v[84:85]
	v_pk_mul_f32 v[18:19], v[18:19], v[82:83]
	v_pk_mul_f32 v[36:37], v[36:37], v[84:85]
	v_pk_mul_f32 v[34:35], v[34:35], v[82:83]
	v_pk_mul_f32 v[238:239], v[238:239], v[84:85]
	v_pk_mul_f32 v[236:237], v[236:237], v[82:83]
	v_pk_mul_f32 v[202:203], v[202:203], v[84:85]
	v_pk_mul_f32 v[200:201], v[200:201], v[82:83]

; #define SBAR() __builtin_amdgcn_sched_barrier(0)
;   #define PKW(P,B) cvtpk_s(P[B],P[B+1])
; template<int THRL> __device__ __forceinline__ void attn_unit(long rowbase,int qb,int t0,bool WIN,bool NOMAX,const bf16*Qc,const bf16*__restrict__ Kc,const bf16*__restrict__ Vc,bf16*Oc,float s2,float sink2,char*shm,
;     bf16x8 (&qr)[4],bool pref,const bf16*qkvb,int vn,int in_){
;     ...
;   { float sacc=pB0[0]+pB0[1]; _Pragma("unroll") for(int r=2;r<16;++r)sacc+=pB0[r]; _Pragma("unroll") for(int r=0;r<16;++r)sacc+=pB1[r]; l_reg+=sacc;
;     pw0=(u32x4){PKW(pB0,0),PKW(pB0,2),PKW(pB0,4),PKW(pB0,6)};pw1=(u32x4){PKW(pB0,8),PKW(pB0,10),PKW(pB0,12),PKW(pB0,14)};pw2=(u32x4){PKW(pB1,0),PKW(pB1,2),PKW(pB1,4),PKW(pB1,6)};pw3=(u32x4){PKW(pB1,8),PKW(pB1,10),PKW(pB1,12),PKW(pB1,14)};
;     SBAR(); pv(o,vb0+sl_cur,PAF(0),PAF(1),PAF(2),PAF(3)); }
;     ...
;   {auto rr=__builtin_amdgcn_permlane32_swap(__float_as_uint(l_reg),__float_as_uint(l_reg),false,false);l_reg=__uint_as_float(rr[0])+__uint_as_float(rr[1]);}
;   l_reg+=__builtin_amdgcn_exp2f(sink2-mhat);
;   if(hi==0)wsf[32+r32]=l_reg;asm volatile("s_waitcnt lgkmcnt(0)":::"memory");
.LBB0_621:
	v_add_f32_e32 v0, v66, v67
	v_add_f32_e32 v0, v68, v0
	v_add_f32_e32 v0, v69, v0
	v_add_f32_e32 v0, v70, v0
	v_add_f32_e32 v0, v71, v0
	v_add_f32_e32 v0, v72, v0
	v_add_f32_e32 v0, v73, v0
	v_add_f32_e32 v0, v74, v0
	v_add_f32_e32 v0, v75, v0
	v_add_f32_e32 v0, v76, v0
	v_add_f32_e32 v0, v77, v0
	v_add_f32_e32 v0, v78, v0
	v_add_f32_e32 v0, v79, v0
	v_add_f32_e32 v0, v80, v0
	v_add_f32_e32 v0, v81, v0
	v_add_f32_e32 v0, v50, v0
	v_add_f32_e32 v0, v51, v0
	v_add_f32_e32 v0, v52, v0
	v_add_f32_e32 v0, v53, v0
	v_add_f32_e32 v0, v54, v0
	v_add_f32_e32 v0, v55, v0
	v_add_f32_e32 v0, v56, v0
	v_add_f32_e32 v0, v57, v0
	v_add_f32_e32 v0, v58, v0
	v_add_f32_e32 v0, v59, v0
	v_add_f32_e32 v0, v60, v0
	v_add_f32_e32 v0, v61, v0
	v_add_f32_e32 v0, v62, v0
	v_add_f32_e32 v0, v63, v0
	s_cmp_lg_u32 0, -1
	v_add_f32_e32 v0, v64, v0
	s_cselect_b32 s2, 0, 0
	v_add_f32_e32 v0, v65, v0
	s_addk_i32 s2, 0x6000
	v_add_f32_e32 v0, v122, v0
	v_cvt_pk_bf16_f32 v50, v50, v51
	v_add3_u32 v82, v229, s2, v219
	v_cvt_pk_bf16_f32 v66, v66, v67
	v_cvt_pk_bf16_f32 v67, v68, v69
	v_cvt_pk_bf16_f32 v68, v70, v71
	v_cvt_pk_bf16_f32 v69, v72, v73
	v_cvt_pk_bf16_f32 v70, v74, v75
	v_cvt_pk_bf16_f32 v71, v76, v77
	v_cvt_pk_bf16_f32 v72, v78, v79
	v_cvt_pk_bf16_f32 v73, v80, v81
	v_cvt_pk_bf16_f32 v51, v52, v53
	v_cvt_pk_bf16_f32 v52, v54, v55
	v_cvt_pk_bf16_f32 v53, v56, v57
	v_cvt_pk_bf16_f32 v54, v58, v59
	v_cvt_pk_bf16_f32 v55, v60, v61
	v_cvt_pk_bf16_f32 v56, v62, v63
	v_cvt_pk_bf16_f32 v57, v64, v65
	v_add3_u32 v82, v82, v226, s86
	s_cmp_gt_u32 s85, 8
	s_cbranch_scc1 .Lmy_nt_drain
	v_add_u32_e32 v255, 0xe800, v82
	ds_read_b64_tr_b16 v[84:85], v255 offset:0
	ds_read_b64_tr_b16 v[86:87], v255 offset:512
	ds_read_b64_tr_b16 v[88:89], v255 offset:1024
	ds_read_b64_tr_b16 v[90:91], v255 offset:1536
	ds_read_b64_tr_b16 v[92:93], v255 offset:2048
	ds_read_b64_tr_b16 v[94:95], v255 offset:2560
	ds_read_b64_tr_b16 v[96:97], v255 offset:3072
	ds_read_b64_tr_b16 v[98:99], v255 offset:3584
	s_waitcnt lgkmcnt(0)
	v_mfma_f32_32x32x16_bf16 v[236:251], v[66:69], v[84:87], v[236:251]
	v_mfma_f32_32x32x16_bf16 v[236:251], v[70:73], v[88:91], v[236:251]
	v_mfma_f32_32x32x16_bf16 v[236:251], v[50:53], v[92:95], v[236:251]
	v_mfma_f32_32x32x16_bf16 v[236:251], v[54:57], v[96:99], v[236:251]
	ds_read_b64_tr_b16 v[84:85], v255 offset:4096
	ds_read_b64_tr_b16 v[86:87], v255 offset:4608
	ds_read_b64_tr_b16 v[88:89], v255 offset:5120
	ds_read_b64_tr_b16 v[90:91], v255 offset:5632
	ds_read_b64_tr_b16 v[92:93], v255 offset:6144
	ds_read_b64_tr_b16 v[94:95], v255 offset:6656
	ds_read_b64_tr_b16 v[96:97], v255 offset:7168
	ds_read_b64_tr_b16 v[98:99], v255 offset:7680
	s_waitcnt lgkmcnt(0)
	v_mfma_f32_32x32x16_bf16 v[200:215], v[66:69], v[84:87], v[200:215]
	v_mfma_f32_32x32x16_bf16 v[200:215], v[70:73], v[88:91], v[200:215]
	v_mfma_f32_32x32x16_bf16 v[200:215], v[50:53], v[92:95], v[200:215]
	v_mfma_f32_32x32x16_bf16 v[200:215], v[54:57], v[96:99], v[200:215]
.Lmy_nt_drain:
	ds_read_b64_tr_b16 v[58:59],v82 offset:0
	ds_read_b64_tr_b16 v[60:61],v82 offset:512
	ds_read_b64_tr_b16 v[62:63],v82 offset:1024
	ds_read_b64_tr_b16 v[64:65],v82 offset:1536
	ds_read_b64_tr_b16 v[74:75],v82 offset:2048
	ds_read_b64_tr_b16 v[76:77],v82 offset:2560
	ds_read_b64_tr_b16 v[78:79],v82 offset:3072
	ds_read_b64_tr_b16 v[80:81],v82 offset:3584
	s_waitcnt lgkmcnt(0)
	s_nop 0
	v_mfma_f32_32x32x16_bf16 v[18:33], v[66:69], v[58:61], v[18:33]
	ds_read_b64_tr_b16 v[58:59],v82 offset:4096
	ds_read_b64_tr_b16 v[60:61],v82 offset:4608
	v_mfma_f32_32x32x16_bf16 v[18:33], v[70:73], v[62:65], v[18:33]
	ds_read_b64_tr_b16 v[62:63],v82 offset:5120
	ds_read_b64_tr_b16 v[64:65],v82 offset:5632
	v_mfma_f32_32x32x16_bf16 v[18:33], v[50:53], v[74:77], v[18:33]
	ds_read_b64_tr_b16 v[74:75],v82 offset:6144
	ds_read_b64_tr_b16 v[76:77],v82 offset:6656
	v_mfma_f32_32x32x16_bf16 v[18:33], v[54:57], v[78:81], v[18:33]
	ds_read_b64_tr_b16 v[78:79],v82 offset:7168
	ds_read_b64_tr_b16 v[80:81],v82 offset:7680
	s_waitcnt lgkmcnt(0)
	v_mfma_f32_32x32x16_bf16 v[34:49], v[66:69], v[58:61], v[34:49]
	v_cmp_gt_u32_e32 vcc, 32, v183
	v_mfma_f32_32x32x16_bf16 v[34:49], v[70:73], v[62:65], v[34:49]
	v_mfma_f32_32x32x16_bf16 v[34:49], v[50:53], v[74:77], v[34:49]
	v_mov_b32_e32 v50, v0
	s_nop 1
	v_permlane32_swap_b32_e32 v0, v50
	v_mfma_f32_32x32x16_bf16 v[34:49], v[54:57], v[78:81], v[34:49]
	s_and_saveexec_b64 s[42:43], vcc
	s_cbranch_execz .LBB0_248
	v_sub_f32_e32 v51, v235, v225
	v_exp_f32_e32 v51, v51
	v_add_f32_e32 v0, v0, v50
	v_add_f32_e32 v0, v51, v0
	ds_write_b32 v228, v0 offset:49280
	s_branch .LBB0_248
